# P6: K-tile loads batched 8-deep and SPREV cross-term loads through a 15-deep register ring
# baseline (speedup 1.0000x reference)
; __device__ __forceinline__ int crow(int r, int hi) { return (r & 3) + 8 * (r >> 2) + 4 * hi; }
; #define MFMA32(a, b, c) __builtin_amdgcn_mfma_f32_32x32x16_bf16((a), (b), (c), 0, 0, 0)
; __device__ __forceinline__ void ro_item2(int it0, LAS unsigned char* lds, const bf16_t* RQ, const bf16_t* RK, const bf16_t* RV, const bf16_t* RG, const bf16_t* SPREV, const float* GN, bf16_t* MIX,
;                                          int tid, int wid, int lane) {
;     ...
;     for (int jt = 0; jt <= ct; ++jt) {
;         f32x16 st = {};
;         const bf16_t* kptr = RK + (r0 + 32 * jt + x) * 1024 + h * 128 + 8 * hi;
; #pragma unroll
;         for (int ks = 0; ks < 8; ++ks) st = MFMA32(*(const bf16x8*)(kptr + 16 * ks), qf[ks], st);
;         if (jt == ct) {
; #pragma unroll
;             for (int r = 0; r < 16; ++r) if (crow(r, hi) > x) st[r] = 0.f;
;         }
; #pragma unroll
;         for (int s2 = 0; s2 < 2; ++s2) {
;             const bf16x8 pb = pack8(st, s2);
; #pragma unroll
;             for (int et = 0; et < 4; ++et) o[et] = MFMA32(lds_cat_sw<VS>(VT, 32 * et + x, 32 * jt + 16 * s2 + 4 * hi), pb, o[et]);
;         }
;     }
;     const bf16_t* sp = SPREV + (size_t)it * 16384;
; #pragma unroll
;     for (int et = 0; et < 4; ++et)
; #pragma unroll
;         for (int ks = 0; ks < 8; ++ks) o[et] = MFMA32(*(const bf16x8*)(sp + (32 * et + x) * 128 + 16 * ks + 8 * hi), qf[ks], o[et]);
.LBB0_1219:
	v_mov_b32_e32 v68, s53
	v_or3_b32 v69, s48, 0, 0
	v_or3_b32 v68, s35, v126, v68
	v_lshl_add_u64 v[66:67], v[130:131], 0, s[42:43]
	v_lshlrev_b64 v[68:69], 11, v[68:69]
	v_lshl_add_u64 v[146:147], v[66:67], 0, v[68:69]
	s_ashr_i32 s35, s34, 31
	s_lshl_b64 s[34:35], s[34:35], 15
	s_add_i32 s50, s50, s54
	s_add_i32 s55, s55, s56
	s_add_i32 s57, s57, s58
	s_mov_b64 s[100:101], 0x2000
	v_lshl_add_u64 v[184:185], v[134:135], 0, s[34:35]
	v_lshl_add_u64 v[186:187], v[184:185], 0, s[100:101]
	v_lshl_add_u64 v[188:189], v[186:187], 0, s[100:101]
	v_lshl_add_u64 v[252:253], v[188:189], 0, s[100:101]
	global_load_dwordx4 v[192:195], v[184:185], off
	global_load_dwordx4 v[196:199], v[184:185], off offset:32
	global_load_dwordx4 v[200:203], v[184:185], off offset:64
	global_load_dwordx4 v[204:207], v[184:185], off offset:96
	global_load_dwordx4 v[208:211], v[184:185], off offset:128
	global_load_dwordx4 v[212:215], v[184:185], off offset:160
	global_load_dwordx4 v[216:219], v[184:185], off offset:192
	global_load_dwordx4 v[220:223], v[146:147], off
	global_load_dwordx4 v[224:227], v[146:147], off offset:32
	global_load_dwordx4 v[228:231], v[146:147], off offset:64
	global_load_dwordx4 v[232:235], v[146:147], off offset:96
	global_load_dwordx4 v[236:239], v[146:147], off offset:128
	global_load_dwordx4 v[240:243], v[146:147], off offset:160
	global_load_dwordx4 v[244:247], v[146:147], off offset:192
	global_load_dwordx4 v[248:251], v[146:147], off offset:224
	s_waitcnt vmcnt(7)
	v_mfma_f32_32x32x16_bf16 v[66:81], v[220:223], v[110:113], 0
	s_waitcnt vmcnt(6)
	v_mfma_f32_32x32x16_bf16 v[66:81], v[224:227], v[106:109], v[66:81]
	s_waitcnt vmcnt(5)
	v_mfma_f32_32x32x16_bf16 v[66:81], v[228:231], v[102:105], v[66:81]
	s_waitcnt vmcnt(4)
	v_mfma_f32_32x32x16_bf16 v[66:81], v[232:235], v[98:101], v[66:81]
	s_waitcnt vmcnt(3)
	v_mfma_f32_32x32x16_bf16 v[66:81], v[236:239], v[94:97], v[66:81]
	s_waitcnt vmcnt(2)
	v_mfma_f32_32x32x16_bf16 v[66:81], v[240:243], v[90:93], v[66:81]
	s_waitcnt vmcnt(1)
	v_mfma_f32_32x32x16_bf16 v[66:81], v[244:247], v[86:89], v[66:81]
	s_waitcnt vmcnt(0)
	v_mfma_f32_32x32x16_bf16 v[66:81], v[248:251], v[82:85], v[66:81]
	global_load_dwordx4 v[220:223], v[184:185], off offset:224
	global_load_dwordx4 v[224:227], v[186:187], off
	global_load_dwordx4 v[228:231], v[186:187], off offset:32
	global_load_dwordx4 v[232:235], v[186:187], off offset:64
	global_load_dwordx4 v[236:239], v[186:187], off offset:96
	global_load_dwordx4 v[240:243], v[186:187], off offset:128
	global_load_dwordx4 v[244:247], v[186:187], off offset:160
	global_load_dwordx4 v[248:251], v[186:187], off offset:192
	s_nop 11
	v_cndmask_b32_e64 v141, v66, 0, s[0:1]
	v_cndmask_b32_e64 v66, v141, v66, s[2:3]
	v_cndmask_b32_e64 v67, 0, v67, s[2:3]
	v_cndmask_b32_e64 v68, v68, 0, s[4:5]
	v_cndmask_b32_e64 v69, v69, 0, s[6:7]
	v_cndmask_b32_e64 v70, v70, 0, s[8:9]
	v_cndmask_b32_e64 v71, v71, 0, s[10:11]
	v_cndmask_b32_e64 v72, v72, 0, s[12:13]
	v_cndmask_b32_e64 v73, v73, 0, s[14:15]
	v_cvt_pk_bf16_f32 v66, v66, v67
	v_cvt_pk_bf16_f32 v67, v68, v69
	v_cvt_pk_bf16_f32 v68, v70, v71
	v_cvt_pk_bf16_f32 v69, v72, v73
	ds_read_b64 v[70:71], v157
	ds_read_b64 v[72:73], v158
	s_waitcnt lgkmcnt(0)
	v_mfma_f32_32x32x16_bf16 v[50:65], v[70:73], v[66:69], v[50:65]
	ds_read_b64 v[70:71], v159
	ds_read_b64 v[72:73], v160
	v_cndmask_b32_e64 v74, v74, 0, s[16:17]
	v_cndmask_b32_e64 v75, v75, 0, s[18:19]
	v_cndmask_b32_e64 v76, v76, 0, s[20:21]
	v_cndmask_b32_e64 v77, v77, 0, s[22:23]
	v_cndmask_b32_e64 v78, v78, 0, s[24:25]
	v_cndmask_b32_e64 v79, v79, 0, s[26:27]
	s_waitcnt lgkmcnt(0)
	v_mfma_f32_32x32x16_bf16 v[34:49], v[70:73], v[66:69], v[34:49]
	ds_read_b64 v[70:71], v161
	ds_read_b64 v[72:73], v162
	v_cndmask_b32_e64 v80, v80, 0, s[28:29]
	v_cndmask_b32_e64 v81, v81, 0, s[30:31]
	v_mov_b32_e32 v141, v115
	s_waitcnt lgkmcnt(0)
	v_mfma_f32_32x32x16_bf16 v[18:33], v[70:73], v[66:69], v[18:33]
	ds_read_b64 v[70:71], v163
	ds_read_b64 v[72:73], v164
	s_waitcnt lgkmcnt(0)
	v_mfma_f32_32x32x16_bf16 v[2:17], v[70:73], v[66:69], v[2:17]
	ds_read_b64 v[70:71], v165
	ds_read_b64 v[72:73], v166
	v_cvt_pk_bf16_f32 v66, v74, v75
	v_cvt_pk_bf16_f32 v67, v76, v77
	v_cvt_pk_bf16_f32 v68, v78, v79
	v_cvt_pk_bf16_f32 v69, v80, v81
	s_waitcnt lgkmcnt(0)
	s_nop 0
	v_mfma_f32_32x32x16_bf16 v[50:65], v[70:73], v[66:69], v[50:65]
	ds_read_b64 v[70:71], v167
	ds_read_b64 v[72:73], v168
	s_waitcnt lgkmcnt(0)
	v_mfma_f32_32x32x16_bf16 v[34:49], v[70:73], v[66:69], v[34:49]
	ds_read_b64 v[70:71], v169
	ds_read_b64 v[72:73], v170
	s_waitcnt lgkmcnt(0)
	v_mfma_f32_32x32x16_bf16 v[18:33], v[70:73], v[66:69], v[18:33]
	ds_read_b64 v[70:71], v171
	ds_read_b64 v[72:73], v172
	s_waitcnt lgkmcnt(0)
	v_mfma_f32_32x32x16_bf16 v[2:17], v[70:73], v[66:69], v[2:17]
	s_waitcnt vmcnt(14)
	v_mfma_f32_32x32x16_bf16 v[50:65], v[192:195], v[110:113], v[50:65]
	global_load_dwordx4 v[192:195], v[186:187], off offset:224
	s_waitcnt vmcnt(14)
	v_mfma_f32_32x32x16_bf16 v[50:65], v[196:199], v[106:109], v[50:65]
	global_load_dwordx4 v[196:199], v[188:189], off
	s_waitcnt vmcnt(14)
	v_mfma_f32_32x32x16_bf16 v[50:65], v[200:203], v[102:105], v[50:65]
	global_load_dwordx4 v[200:203], v[188:189], off offset:32
	s_waitcnt vmcnt(14)
	v_mfma_f32_32x32x16_bf16 v[50:65], v[204:207], v[98:101], v[50:65]
	global_load_dwordx4 v[204:207], v[188:189], off offset:64
	s_waitcnt vmcnt(14)
	v_mfma_f32_32x32x16_bf16 v[50:65], v[208:211], v[94:97], v[50:65]
	global_load_dwordx4 v[208:211], v[188:189], off offset:96
	s_waitcnt vmcnt(14)
	v_mfma_f32_32x32x16_bf16 v[50:65], v[212:215], v[90:93], v[50:65]
	global_load_dwordx4 v[212:215], v[188:189], off offset:128
	s_waitcnt vmcnt(14)
; #define MFMA32(a, b, c) __builtin_amdgcn_mfma_f32_32x32x16_bf16((a), (b), (c), 0, 0, 0)
; __device__ __forceinline__ void ro_item2(int it0, LAS unsigned char* lds, const bf16_t* RQ, const bf16_t* RK, const bf16_t* RV, const bf16_t* RG, const bf16_t* SPREV, const float* GN, bf16_t* MIX,
;                                          int tid, int wid, int lane) {
;     ...
;         for (int ks = 0; ks < 8; ++ks) o[et] = MFMA32(*(const bf16x8*)(sp + (32 * et + x) * 128 + 16 * ks + 8 * hi), qf[ks], o[et]);
;     float s1 = 0.f, s2 = 0.f;
; #pragma unroll
;     for (int et = 0; et < 4; ++et)
; #pragma unroll
;         for (int r = 0; r < 16; ++r) { s1 += o[et][r]; s2 += o[et][r] * o[et][r]; }
	v_mfma_f32_32x32x16_bf16 v[50:65], v[216:219], v[86:89], v[50:65]
	global_load_dwordx4 v[216:219], v[188:189], off offset:160
	s_waitcnt vmcnt(14)
	v_mfma_f32_32x32x16_bf16 v[50:65], v[220:223], v[82:85], v[50:65]
	global_load_dwordx4 v[220:223], v[188:189], off offset:192
	s_waitcnt vmcnt(14)
	v_mfma_f32_32x32x16_bf16 v[34:49], v[224:227], v[110:113], v[34:49]
	global_load_dwordx4 v[224:227], v[188:189], off offset:224
	s_nop 8
	v_mul_f32_e32 v80, v51, v51
	v_fmac_f32_e32 v80, v50, v50
	v_fmac_f32_e32 v80, v52, v52
	v_fmac_f32_e32 v80, v53, v53
	v_fmac_f32_e32 v80, v54, v54
	v_fmac_f32_e32 v80, v55, v55
	v_fmac_f32_e32 v80, v56, v56
	v_fmac_f32_e32 v80, v57, v57
	v_fmac_f32_e32 v80, v58, v58
	v_fmac_f32_e32 v80, v59, v59
	v_fmac_f32_e32 v80, v60, v60
	v_fmac_f32_e32 v80, v61, v61
	v_fmac_f32_e32 v80, v62, v62
	v_fmac_f32_e32 v80, v63, v63
	v_fmac_f32_e32 v80, v64, v64
	v_fmac_f32_e32 v80, v65, v65
	s_waitcnt vmcnt(14)
	v_mfma_f32_32x32x16_bf16 v[34:49], v[228:231], v[106:109], v[34:49]
	global_load_dwordx4 v[228:231], v[252:253], off
	s_waitcnt vmcnt(14)
	v_mfma_f32_32x32x16_bf16 v[34:49], v[232:235], v[102:105], v[34:49]
	global_load_dwordx4 v[232:235], v[252:253], off offset:32
	s_waitcnt vmcnt(14)
	v_mfma_f32_32x32x16_bf16 v[34:49], v[236:239], v[98:101], v[34:49]
	global_load_dwordx4 v[236:239], v[252:253], off offset:64
	s_waitcnt vmcnt(14)
	v_mfma_f32_32x32x16_bf16 v[34:49], v[240:243], v[94:97], v[34:49]
	global_load_dwordx4 v[240:243], v[252:253], off offset:96
	s_waitcnt vmcnt(14)
	v_mfma_f32_32x32x16_bf16 v[34:49], v[244:247], v[90:93], v[34:49]
	global_load_dwordx4 v[244:247], v[252:253], off offset:128
	s_waitcnt vmcnt(14)
	v_mfma_f32_32x32x16_bf16 v[34:49], v[248:251], v[86:89], v[34:49]
	global_load_dwordx4 v[248:251], v[252:253], off offset:160
	s_waitcnt vmcnt(14)
	v_mfma_f32_32x32x16_bf16 v[34:49], v[192:195], v[82:85], v[34:49]
	global_load_dwordx4 v[192:195], v[252:253], off offset:192
	s_waitcnt vmcnt(14)
	v_mfma_f32_32x32x16_bf16 v[18:33], v[196:199], v[110:113], v[18:33]
	global_load_dwordx4 v[196:199], v[252:253], off offset:224
	s_nop 8
	v_fmac_f32_e32 v80, v34, v34
	v_fmac_f32_e32 v80, v35, v35
	v_fmac_f32_e32 v80, v36, v36
	v_fmac_f32_e32 v80, v37, v37
	v_fmac_f32_e32 v80, v38, v38
	v_fmac_f32_e32 v80, v39, v39
	v_fmac_f32_e32 v80, v40, v40
	v_fmac_f32_e32 v80, v41, v41
	v_fmac_f32_e32 v80, v42, v42
	v_fmac_f32_e32 v80, v43, v43
	v_fmac_f32_e32 v80, v44, v44
	v_fmac_f32_e32 v80, v45, v45
	v_fmac_f32_e32 v80, v46, v46
	v_fmac_f32_e32 v80, v47, v47
	v_fmac_f32_e32 v80, v48, v48
	v_fmac_f32_e32 v80, v49, v49
	s_waitcnt vmcnt(14)
	v_mfma_f32_32x32x16_bf16 v[18:33], v[200:203], v[106:109], v[18:33]
	s_waitcnt vmcnt(13)
	v_mfma_f32_32x32x16_bf16 v[18:33], v[204:207], v[102:105], v[18:33]
	s_waitcnt vmcnt(12)
	v_mfma_f32_32x32x16_bf16 v[18:33], v[208:211], v[98:101], v[18:33]
	s_waitcnt vmcnt(11)
	v_mfma_f32_32x32x16_bf16 v[18:33], v[212:215], v[94:97], v[18:33]
	s_waitcnt vmcnt(10)
	v_mfma_f32_32x32x16_bf16 v[18:33], v[216:219], v[90:93], v[18:33]
	s_waitcnt vmcnt(9)
	v_mfma_f32_32x32x16_bf16 v[18:33], v[220:223], v[86:89], v[18:33]
	s_waitcnt vmcnt(8)
	v_mfma_f32_32x32x16_bf16 v[18:33], v[224:227], v[82:85], v[18:33]
	s_waitcnt vmcnt(7)
	v_mfma_f32_32x32x16_bf16 v[2:17], v[228:231], v[110:113], v[2:17]
	s_nop 8
	v_fmac_f32_e32 v80, v18, v18
	v_fmac_f32_e32 v80, v19, v19
	v_fmac_f32_e32 v80, v20, v20
	v_fmac_f32_e32 v80, v21, v21
	v_fmac_f32_e32 v80, v22, v22
	v_fmac_f32_e32 v80, v23, v23
	v_fmac_f32_e32 v80, v24, v24
	v_fmac_f32_e32 v80, v25, v25
	v_fmac_f32_e32 v80, v26, v26
	v_fmac_f32_e32 v80, v27, v27
	v_fmac_f32_e32 v80, v28, v28
	v_fmac_f32_e32 v80, v29, v29
	v_fmac_f32_e32 v80, v30, v30
	v_fmac_f32_e32 v80, v31, v31
	v_fmac_f32_e32 v80, v32, v32
	v_fmac_f32_e32 v80, v33, v33
	s_waitcnt vmcnt(6)
	v_mfma_f32_32x32x16_bf16 v[2:17], v[232:235], v[106:109], v[2:17]
	s_waitcnt vmcnt(5)
	v_mfma_f32_32x32x16_bf16 v[2:17], v[236:239], v[102:105], v[2:17]
	s_waitcnt vmcnt(4)
	v_mfma_f32_32x32x16_bf16 v[2:17], v[240:243], v[98:101], v[2:17]
	s_waitcnt vmcnt(3)
	v_mfma_f32_32x32x16_bf16 v[2:17], v[244:247], v[94:97], v[2:17]
	s_waitcnt vmcnt(2)
	v_mfma_f32_32x32x16_bf16 v[2:17], v[248:251], v[90:93], v[2:17]
	s_waitcnt vmcnt(1)
	v_mfma_f32_32x32x16_bf16 v[2:17], v[192:195], v[86:89], v[2:17]
	s_waitcnt vmcnt(0)
; __device__ __forceinline__ float bflo(unsigned w) { return __uint_as_float(w << 16); }
; __device__ __forceinline__ float bfhi(unsigned w) { return __uint_as_float(w & 0xffff0000u); }
; #define MFMA32(a, b, c) __builtin_amdgcn_mfma_f32_32x32x16_bf16((a), (b), (c), 0, 0, 0)
; __device__ __forceinline__ void ro_item2(int it0, LAS unsigned char* lds, const bf16_t* RQ, const bf16_t* RK, const bf16_t* RV, const bf16_t* RG, const bf16_t* SPREV, const float* GN, bf16_t* MIX,
;                                          int tid, int wid, int lane) {
;     ...
;         for (int ks = 0; ks < 8; ++ks) o[et] = MFMA32(*(const bf16x8*)(sp + (32 * et + x) * 128 + 16 * ks + 8 * hi), qf[ks], o[et]);
;     float s1 = 0.f, s2 = 0.f;
; #pragma unroll
;     for (int et = 0; et < 4; ++et)
; #pragma unroll
;         for (int r = 0; r < 16; ++r) { s1 += o[et][r]; s2 += o[et][r] * o[et][r]; }
;     s1 += __shfl_xor(s1, 32); s2 += __shfl_xor(s2, 32);
;     const float mean = s1 * (1.0f / 128.0f), var = fmaxf(s2 * (1.0f / 128.0f) - mean * mean, 0.f), rstd = rsqrtf(var + EPS);
; #pragma unroll
;     for (int et = 0; et < 4; ++et)
; #pragma unroll
;         for (int g = 0; g < 4; ++g) {
;             const int e0 = 32 * et + 8 * g + 4 * hi;
;             const u32x2 gt = *(const u32x2*)(RG + qrow * 1024 + h * 128 + e0);
;             const f32x4 gn = *(const f32x4*)(GN + h * 128 + e0);
;             const float y0 = (o[et][4 * g] - mean) * rstd * gn[0] * bflo(gt.x), y1 = (o[et][4 * g + 1] - mean) * rstd * gn[1] * bfhi(gt.x);
	v_mfma_f32_32x32x16_bf16 v[2:17], v[196:199], v[82:85], v[2:17]
	s_brev_b32 s34, 60
	v_add_f32_e32 v66, 0, v50
	v_add_f32_e32 v66, v51, v66
	v_add_f32_e32 v66, v52, v66
	v_add_f32_e32 v66, v53, v66
	v_add_f32_e32 v66, v54, v66
	v_add_f32_e32 v66, v55, v66
	v_add_f32_e32 v66, v56, v66
	v_add_f32_e32 v66, v57, v66
	v_add_f32_e32 v66, v58, v66
	v_add_f32_e32 v66, v59, v66
	v_add_f32_e32 v66, v60, v66
	v_add_f32_e32 v66, v61, v66
	v_add_f32_e32 v66, v62, v66
	v_add_f32_e32 v66, v63, v66
	v_add_f32_e32 v66, v64, v66
	v_add_f32_e32 v66, v65, v66
	v_add_f32_e32 v66, v66, v34
	v_add_f32_e32 v66, v35, v66
	v_add_f32_e32 v66, v36, v66
	v_add_f32_e32 v66, v37, v66
	v_add_f32_e32 v66, v38, v66
	v_add_f32_e32 v66, v39, v66
	v_add_f32_e32 v66, v40, v66
	v_add_f32_e32 v66, v41, v66
	v_add_f32_e32 v66, v42, v66
	v_add_f32_e32 v66, v43, v66
	v_add_f32_e32 v66, v44, v66
	v_add_f32_e32 v66, v45, v66
	v_add_f32_e32 v66, v46, v66
	v_add_f32_e32 v66, v47, v66
	v_add_f32_e32 v66, v48, v66
	v_add_f32_e32 v66, v49, v66
	v_add_f32_e32 v66, v66, v18
	v_add_f32_e32 v66, v19, v66
	v_add_f32_e32 v66, v20, v66
	v_add_f32_e32 v66, v21, v66
	v_add_f32_e32 v66, v22, v66
	v_add_f32_e32 v66, v23, v66
	v_add_f32_e32 v66, v24, v66
	v_add_f32_e32 v66, v25, v66
	v_add_f32_e32 v66, v26, v66
	v_add_f32_e32 v66, v27, v66
	v_add_f32_e32 v66, v28, v66
	v_add_f32_e32 v66, v29, v66
	v_add_f32_e32 v66, v30, v66
	v_add_f32_e32 v66, v31, v66
	v_add_f32_e32 v66, v32, v66
	v_add_f32_e32 v66, v33, v66
	v_add_f32_e32 v66, v66, v2
	v_add_f32_e32 v66, v3, v66
	v_fmac_f32_e32 v80, v2, v2
	v_add_f32_e32 v66, v4, v66
	v_fmac_f32_e32 v80, v3, v3
	v_add_f32_e32 v66, v5, v66
	v_fmac_f32_e32 v80, v4, v4
	v_add_f32_e32 v81, v6, v66
	v_pk_mul_f32 v[66:67], v[16:17], v[16:17]
	v_pk_mul_f32 v[78:79], v[4:5], v[4:5]
	v_pk_mul_f32 v[76:77], v[6:7], v[6:7]
	v_add_f32_e32 v67, v79, v80
	v_add_f32_e32 v67, v76, v67
	v_pk_mul_f32 v[74:75], v[8:9], v[8:9]
	v_add_f32_e32 v76, v7, v81
	v_add_f32_e32 v67, v77, v67
	v_add_f32_e32 v76, v8, v76
	v_add_f32_e32 v67, v74, v67
	v_pk_mul_f32 v[72:73], v[10:11], v[10:11]
	v_add_f32_e32 v74, v9, v76
	v_add_f32_e32 v67, v75, v67
	v_add_f32_e32 v74, v10, v74
	v_add_f32_e32 v67, v72, v67
	v_pk_mul_f32 v[70:71], v[12:13], v[12:13]
	v_add_f32_e32 v72, v11, v74
	v_add_f32_e32 v67, v73, v67
	v_add_f32_e32 v72, v12, v72
	v_add_f32_e32 v67, v70, v67
	v_pk_mul_f32 v[68:69], v[14:15], v[14:15]
	v_add_f32_e32 v70, v13, v72
	v_add_f32_e32 v67, v71, v67
	v_add_f32_e32 v70, v14, v70
	v_add_f32_e32 v68, v68, v67
	v_add_f32_e32 v67, v15, v70
	v_add_f32_e32 v68, v69, v68
	v_add_f32_e32 v67, v16, v67
	v_add_f32_e32 v68, v66, v68
	v_mul_f32_e32 v66, v17, v17
	v_mov_b32_e32 v69, v17
	v_pk_add_f32 v[66:67], v[68:69], v[66:67]
	ds_bpermute_b32 v69, v173, v67
	ds_bpermute_b32 v68, v173, v66
	s_waitcnt lgkmcnt(0)
	v_pk_add_f32 v[66:67], v[66:67], v[68:69]
	s_nop 0
	v_pk_mul_f32 v[70:71], v[66:67], s[34:35] op_sel_hi:[1,0]
	s_mov_b32 s34, 0x800000
	v_fma_f32 v66, -v71, v71, v70
	v_max_f32_e32 v66, 0, v66
	v_add_f32_e32 v66, 0x358637bd, v66
	v_cmp_gt_f32_e32 vcc, s34, v66
	v_mul_f32_e32 v67, 0x4b800000, v66
	v_readlane_b32 s34, v254, 54
	v_cndmask_b32_e32 v66, v66, v67, vcc
	v_rsq_f32_e32 v66, v66
	v_readlane_b32 s35, v254, 55
	v_lshlrev_b64 v[68:69], 12, v[142:143]
	v_lshl_add_u64 v[68:69], s[38:39], 0, v[68:69]
	v_mul_f32_e32 v67, 0x45800000, v66
	v_cndmask_b32_e32 v72, v66, v67, vcc
	v_lshl_add_u64 v[66:67], s[34:35], 0, v[144:145]
	v_lshl_add_u64 v[66:67], v[66:67], 0, s[42:43]
	v_lshl_add_u64 v[78:79], v[68:69], 0, s[42:43]
	s_lshl_b32 s42, s33, 2
	v_lshl_add_u64 v[76:77], v[66:67], 0, v[140:141]
	v_lshl_add_u64 v[74:75], v[136:137], 0, s[42:43]
	global_load_dwordx2 v[80:81], v[76:77], off
	global_load_dwordx4 v[66:69], v[74:75], off
	v_pk_add_f32 v[50:51], v[50:51], v[70:71] op_sel:[0,1] neg_lo:[0,1] neg_hi:[0,1]
	v_pk_add_f32 v[52:53], v[52:53], v[70:71] op_sel:[0,1] neg_lo:[0,1] neg_hi:[0,1]
	v_pk_mul_f32 v[50:51], v[50:51], v[72:73] op_sel_hi:[1,0]
	v_pk_mul_f32 v[52:53], v[52:53], v[72:73] op_sel_hi:[1,0]
	v_pk_add_f32 v[54:55], v[54:55], v[70:71] op_sel:[0,1] neg_lo:[0,1] neg_hi:[0,1]
	v_pk_add_f32 v[56:57], v[56:57], v[70:71] op_sel:[0,1] neg_lo:[0,1] neg_hi:[0,1]
	v_pk_mul_f32 v[54:55], v[54:55], v[72:73] op_sel_hi:[1,0]
	v_pk_mul_f32 v[56:57], v[56:57], v[72:73] op_sel_hi:[1,0]
	v_pk_add_f32 v[58:59], v[58:59], v[70:71] op_sel:[0,1] neg_lo:[0,1] neg_hi:[0,1]
	v_pk_add_f32 v[34:35], v[34:35], v[70:71] op_sel:[0,1] neg_lo:[0,1] neg_hi:[0,1]
	v_pk_mul_f32 v[58:59], v[58:59], v[72:73] op_sel_hi:[1,0]
	v_pk_mul_f32 v[34:35], v[34:35], v[72:73] op_sel_hi:[1,0]
	v_pk_add_f32 v[36:37], v[36:37], v[70:71] op_sel:[0,1] neg_lo:[0,1] neg_hi:[0,1]
	v_pk_add_f32 v[38:39], v[38:39], v[70:71] op_sel:[0,1] neg_lo:[0,1] neg_hi:[0,1]
	v_pk_mul_f32 v[36:37], v[36:37], v[72:73] op_sel_hi:[1,0]
	v_pk_mul_f32 v[38:39], v[38:39], v[72:73] op_sel_hi:[1,0]
	v_pk_add_f32 v[18:19], v[18:19], v[70:71] op_sel:[0,1] neg_lo:[0,1] neg_hi:[0,1]
	v_pk_add_f32 v[20:21], v[20:21], v[70:71] op_sel:[0,1] neg_lo:[0,1] neg_hi:[0,1]
	v_pk_mul_f32 v[18:19], v[18:19], v[72:73] op_sel_hi:[1,0]
	v_pk_mul_f32 v[20:21], v[20:21], v[72:73] op_sel_hi:[1,0]
	v_pk_add_f32 v[22:23], v[22:23], v[70:71] op_sel:[0,1] neg_lo:[0,1] neg_hi:[0,1]
	v_pk_add_f32 v[2:3], v[2:3], v[70:71] op_sel:[0,1] neg_lo:[0,1] neg_hi:[0,1]
	v_pk_mul_f32 v[22:23], v[22:23], v[72:73] op_sel_hi:[1,0]
	v_pk_mul_f32 v[2:3], v[2:3], v[72:73] op_sel_hi:[1,0]
	v_pk_add_f32 v[4:5], v[4:5], v[70:71] op_sel:[0,1] neg_lo:[0,1] neg_hi:[0,1]
	v_pk_add_f32 v[6:7], v[6:7], v[70:71] op_sel:[0,1] neg_lo:[0,1] neg_hi:[0,1]
	v_pk_mul_f32 v[4:5], v[4:5], v[72:73] op_sel_hi:[1,0]
	v_pk_mul_f32 v[6:7], v[6:7], v[72:73] op_sel_hi:[1,0]
	s_cmpk_lt_i32 s50, 0x200
	s_waitcnt vmcnt(0)
; __device__ __forceinline__ unsigned cvtpk(float lo, float hi) { f32x2_t v = {lo, hi}; bf16x2_t b = __builtin_convertvector(v, bf16x2_t); return __builtin_bit_cast(unsigned, b); }
; __device__ __forceinline__ float bflo(unsigned w) { return __uint_as_float(w << 16); }
; __device__ __forceinline__ float bfhi(unsigned w) { return __uint_as_float(w & 0xffff0000u); }
; __device__ __forceinline__ void ro_item2(int it0, LAS unsigned char* lds, const bf16_t* RQ, const bf16_t* RK, const bf16_t* RV, const bf16_t* RG, const bf16_t* SPREV, const float* GN, bf16_t* MIX,
;                                          int tid, int wid, int lane) {
;     ...
; #pragma unroll
;     for (int et = 0; et < 4; ++et)
; #pragma unroll
;         for (int g = 0; g < 4; ++g) {
;             const int e0 = 32 * et + 8 * g + 4 * hi;
;             const u32x2 gt = *(const u32x2*)(RG + qrow * 1024 + h * 128 + e0);
;             const f32x4 gn = *(const f32x4*)(GN + h * 128 + e0);
;             const float y0 = (o[et][4 * g] - mean) * rstd * gn[0] * bflo(gt.x), y1 = (o[et][4 * g + 1] - mean) * rstd * gn[1] * bfhi(gt.x);
;             const float y2 = (o[et][4 * g + 2] - mean) * rstd * gn[2] * bflo(gt.y), y3 = (o[et][4 * g + 3] - mean) * rstd * gn[3] * bfhi(gt.y);
;             u32x2 w; w.x = cvtpk(y0, y1); w.y = cvtpk(y2, y3);
;             *(u32x2*)(MIX + qrow * 2048 + h * 128 + e0) = w;
;         }
	v_pk_mul_f32 v[50:51], v[66:67], v[50:51]
	v_lshlrev_b32_e32 v66, 16, v80
	v_and_b32_e32 v67, 0xffff0000, v80
	v_pk_mul_f32 v[50:51], v[50:51], v[66:67]
	v_pk_mul_f32 v[52:53], v[68:69], v[52:53]
	v_lshlrev_b32_e32 v66, 16, v81
	v_and_b32_e32 v67, 0xffff0000, v81
	v_pk_mul_f32 v[52:53], v[52:53], v[66:67]
	v_cvt_pk_bf16_f32 v66, v50, v51
	v_cvt_pk_bf16_f32 v67, v52, v53
	v_lshl_add_u64 v[50:51], v[78:79], 0, v[140:141]
	global_store_dwordx2 v[50:51], v[66:67], off
	global_load_dwordx2 v[52:53], v[76:77], off offset:16
	s_nop 0
	global_load_dwordx4 v[66:69], v[74:75], off offset:32
	s_waitcnt vmcnt(0)
	v_pk_mul_f32 v[54:55], v[66:67], v[54:55]
	v_lshlrev_b32_e32 v66, 16, v52
	v_and_b32_e32 v67, 0xffff0000, v52
	v_pk_mul_f32 v[56:57], v[68:69], v[56:57]
	v_lshlrev_b32_e32 v52, 16, v53
	v_and_b32_e32 v53, 0xffff0000, v53
	v_pk_mul_f32 v[54:55], v[54:55], v[66:67]
	v_pk_mul_f32 v[52:53], v[56:57], v[52:53]
	v_cvt_pk_bf16_f32 v54, v54, v55
	v_cvt_pk_bf16_f32 v55, v52, v53
	global_store_dwordx2 v[50:51], v[54:55], off offset:16
	global_load_dwordx2 v[56:57], v[76:77], off offset:32
	s_nop 0
	global_load_dwordx4 v[52:55], v[74:75], off offset:64
	s_waitcnt vmcnt(0)
	v_pk_mul_f32 v[52:53], v[52:53], v[58:59]
	v_lshlrev_b32_e32 v58, 16, v56
	v_and_b32_e32 v59, 0xffff0000, v56
	v_pk_mul_f32 v[52:53], v[52:53], v[58:59]
	v_pk_add_f32 v[58:59], v[60:61], v[70:71] op_sel:[0,1] neg_lo:[0,1] neg_hi:[0,1]
	v_lshlrev_b32_e32 v56, 16, v57
	v_pk_mul_f32 v[58:59], v[58:59], v[72:73] op_sel_hi:[1,0]
	v_and_b32_e32 v57, 0xffff0000, v57
	v_pk_mul_f32 v[54:55], v[54:55], v[58:59]
	v_cvt_pk_bf16_f32 v52, v52, v53
	v_pk_mul_f32 v[54:55], v[54:55], v[56:57]
	v_pk_add_f32 v[58:59], v[62:63], v[70:71] op_sel:[0,1] neg_lo:[0,1] neg_hi:[0,1]
	v_cvt_pk_bf16_f32 v53, v54, v55
	global_store_dwordx2 v[50:51], v[52:53], off offset:32
	global_load_dwordx2 v[56:57], v[76:77], off offset:48
	s_nop 0
	global_load_dwordx4 v[52:55], v[74:75], off offset:96
	v_pk_mul_f32 v[58:59], v[58:59], v[72:73] op_sel_hi:[1,0]
	s_waitcnt vmcnt(0)
	v_pk_mul_f32 v[52:53], v[52:53], v[58:59]
	v_lshlrev_b32_e32 v58, 16, v56
	v_and_b32_e32 v59, 0xffff0000, v56
	v_pk_mul_f32 v[52:53], v[52:53], v[58:59]
	v_pk_add_f32 v[58:59], v[64:65], v[70:71] op_sel:[0,1] neg_lo:[0,1] neg_hi:[0,1]
	v_lshlrev_b32_e32 v56, 16, v57
	v_pk_mul_f32 v[58:59], v[58:59], v[72:73] op_sel_hi:[1,0]
	v_and_b32_e32 v57, 0xffff0000, v57
	v_pk_mul_f32 v[54:55], v[54:55], v[58:59]
	v_cvt_pk_bf16_f32 v52, v52, v53
	v_pk_mul_f32 v[54:55], v[54:55], v[56:57]
	s_nop 0
	v_cvt_pk_bf16_f32 v53, v54, v55
	global_store_dwordx2 v[50:51], v[52:53], off offset:48
	global_load_dwordx2 v[56:57], v[76:77], off offset:64
	s_nop 0
	global_load_dwordx4 v[52:55], v[74:75], off offset:128
	s_waitcnt vmcnt(0)
	v_pk_mul_f32 v[34:35], v[52:53], v[34:35]
	v_lshlrev_b32_e32 v52, 16, v56
	v_and_b32_e32 v53, 0xffff0000, v56
	v_pk_mul_f32 v[34:35], v[34:35], v[52:53]
	v_pk_mul_f32 v[36:37], v[54:55], v[36:37]
	v_lshlrev_b32_e32 v52, 16, v57
	v_and_b32_e32 v53, 0xffff0000, v57
	v_pk_mul_f32 v[36:37], v[36:37], v[52:53]
	v_cvt_pk_bf16_f32 v34, v34, v35
	v_cvt_pk_bf16_f32 v35, v36, v37
	global_store_dwordx2 v[50:51], v[34:35], off offset:64
	global_load_dwordx2 v[52:53], v[76:77], off offset:80
	s_nop 0
	global_load_dwordx4 v[34:37], v[74:75], off offset:160
	s_waitcnt vmcnt(0)
	v_pk_mul_f32 v[34:35], v[34:35], v[38:39]
	v_lshlrev_b32_e32 v38, 16, v52
	v_and_b32_e32 v39, 0xffff0000, v52
	v_pk_mul_f32 v[34:35], v[34:35], v[38:39]
	v_pk_add_f32 v[38:39], v[40:41], v[70:71] op_sel:[0,1] neg_lo:[0,1] neg_hi:[0,1]
	v_cvt_pk_bf16_f32 v34, v34, v35
	v_pk_mul_f32 v[38:39], v[38:39], v[72:73] op_sel_hi:[1,0]
	v_pk_add_f32 v[40:41], v[42:43], v[70:71] op_sel:[0,1] neg_lo:[0,1] neg_hi:[0,1]
	v_pk_mul_f32 v[36:37], v[36:37], v[38:39]
	v_lshlrev_b32_e32 v38, 16, v53
	v_and_b32_e32 v39, 0xffff0000, v53
	v_pk_mul_f32 v[36:37], v[36:37], v[38:39]
	v_pk_mul_f32 v[40:41], v[40:41], v[72:73] op_sel_hi:[1,0]
	v_cvt_pk_bf16_f32 v35, v36, v37
	global_store_dwordx2 v[50:51], v[34:35], off offset:80
	global_load_dwordx2 v[38:39], v[76:77], off offset:96
	s_nop 0
	global_load_dwordx4 v[34:37], v[74:75], off offset:192
	s_waitcnt vmcnt(0)
	v_pk_mul_f32 v[34:35], v[34:35], v[40:41]
	v_lshlrev_b32_e32 v40, 16, v38
	v_and_b32_e32 v41, 0xffff0000, v38
	v_pk_mul_f32 v[34:35], v[34:35], v[40:41]
	v_pk_add_f32 v[40:41], v[44:45], v[70:71] op_sel:[0,1] neg_lo:[0,1] neg_hi:[0,1]
	v_lshlrev_b32_e32 v38, 16, v39
	v_pk_mul_f32 v[40:41], v[40:41], v[72:73] op_sel_hi:[1,0]
	v_and_b32_e32 v39, 0xffff0000, v39
	v_pk_mul_f32 v[36:37], v[36:37], v[40:41]
	v_cvt_pk_bf16_f32 v34, v34, v35
	v_pk_mul_f32 v[36:37], v[36:37], v[38:39]
	v_pk_add_f32 v[40:41], v[46:47], v[70:71] op_sel:[0,1] neg_lo:[0,1] neg_hi:[0,1]
	v_cvt_pk_bf16_f32 v35, v36, v37
	global_store_dwordx2 v[50:51], v[34:35], off offset:96
	global_load_dwordx2 v[38:39], v[76:77], off offset:112
	s_nop 0
	global_load_dwordx4 v[34:37], v[74:75], off offset:224
	v_pk_mul_f32 v[40:41], v[40:41], v[72:73] op_sel_hi:[1,0]
	s_waitcnt vmcnt(0)
	v_pk_mul_f32 v[34:35], v[34:35], v[40:41]
	v_lshlrev_b32_e32 v40, 16, v38
	v_and_b32_e32 v41, 0xffff0000, v38
	v_pk_mul_f32 v[34:35], v[34:35], v[40:41]
	v_pk_add_f32 v[40:41], v[48:49], v[70:71] op_sel:[0,1] neg_lo:[0,1] neg_hi:[0,1]
	v_lshlrev_b32_e32 v38, 16, v39
	v_pk_mul_f32 v[40:41], v[40:41], v[72:73] op_sel_hi:[1,0]
	v_and_b32_e32 v39, 0xffff0000, v39
	v_pk_mul_f32 v[36:37], v[36:37], v[40:41]
	v_cvt_pk_bf16_f32 v34, v34, v35
	v_pk_mul_f32 v[36:37], v[36:37], v[38:39]
	s_nop 0
	v_cvt_pk_bf16_f32 v35, v36, v37
	global_store_dwordx2 v[50:51], v[34:35], off offset:112
	global_load_dwordx2 v[38:39], v[76:77], off offset:128
	s_nop 0
	global_load_dwordx4 v[34:37], v[74:75], off offset:256
	s_waitcnt vmcnt(0)
; __device__ __forceinline__ unsigned cvtpk(float lo, float hi) { f32x2_t v = {lo, hi}; bf16x2_t b = __builtin_convertvector(v, bf16x2_t); return __builtin_bit_cast(unsigned, b); }
; __device__ __forceinline__ float bflo(unsigned w) { return __uint_as_float(w << 16); }
; __device__ __forceinline__ float bfhi(unsigned w) { return __uint_as_float(w & 0xffff0000u); }
; __device__ __forceinline__ void ro_item2(int it0, LAS unsigned char* lds, const bf16_t* RQ, const bf16_t* RK, const bf16_t* RV, const bf16_t* RG, const bf16_t* SPREV, const float* GN, bf16_t* MIX,
;                                          int tid, int wid, int lane) {
;     ...
; #pragma unroll
;     for (int et = 0; et < 4; ++et)
; #pragma unroll
;         for (int g = 0; g < 4; ++g) {
;             const int e0 = 32 * et + 8 * g + 4 * hi;
;             const u32x2 gt = *(const u32x2*)(RG + qrow * 1024 + h * 128 + e0);
;             const f32x4 gn = *(const f32x4*)(GN + h * 128 + e0);
;             const float y0 = (o[et][4 * g] - mean) * rstd * gn[0] * bflo(gt.x), y1 = (o[et][4 * g + 1] - mean) * rstd * gn[1] * bfhi(gt.x);
;             const float y2 = (o[et][4 * g + 2] - mean) * rstd * gn[2] * bflo(gt.y), y3 = (o[et][4 * g + 3] - mean) * rstd * gn[3] * bfhi(gt.y);
;             u32x2 w; w.x = cvtpk(y0, y1); w.y = cvtpk(y2, y3);
;             *(u32x2*)(MIX + qrow * 2048 + h * 128 + e0) = w;
;         }
; __global__ void __launch_bounds__(512, 2) mk_fwd(Args a) {
;     ...
;     if (IN(6)) { for (int it = 2 * bid; it < 512; it += 2 * G) ro_item2(it, lds, RQ, RK, RV, RG, SPREV, a.in[8], MIX, tid, wid, lane); }
	v_pk_mul_f32 v[18:19], v[18:19], v[34:35]
	v_lshlrev_b32_e32 v34, 16, v38
	v_and_b32_e32 v35, 0xffff0000, v38
	v_pk_mul_f32 v[18:19], v[18:19], v[34:35]
	v_pk_mul_f32 v[20:21], v[20:21], v[36:37]
	v_lshlrev_b32_e32 v34, 16, v39
	v_and_b32_e32 v35, 0xffff0000, v39
	v_pk_mul_f32 v[20:21], v[20:21], v[34:35]
	v_cvt_pk_bf16_f32 v18, v18, v19
	v_cvt_pk_bf16_f32 v19, v20, v21
	global_store_dwordx2 v[50:51], v[18:19], off offset:128
	global_load_dwordx2 v[34:35], v[76:77], off offset:144
	s_nop 0
	global_load_dwordx4 v[18:21], v[74:75], off offset:288
	s_waitcnt vmcnt(0)
	v_pk_mul_f32 v[18:19], v[22:23], v[18:19]
	v_lshlrev_b32_e32 v22, 16, v34
	v_and_b32_e32 v23, 0xffff0000, v34
	v_pk_mul_f32 v[18:19], v[18:19], v[22:23]
	v_pk_add_f32 v[22:23], v[24:25], v[70:71] op_sel:[0,1] neg_lo:[0,1] neg_hi:[0,1]
	v_cvt_pk_bf16_f32 v18, v18, v19
	v_pk_mul_f32 v[22:23], v[22:23], v[72:73] op_sel_hi:[1,0]
	v_pk_add_f32 v[24:25], v[26:27], v[70:71] op_sel:[0,1] neg_lo:[0,1] neg_hi:[0,1]
	v_pk_mul_f32 v[20:21], v[22:23], v[20:21]
	v_lshlrev_b32_e32 v22, 16, v35
	v_and_b32_e32 v23, 0xffff0000, v35
	v_pk_mul_f32 v[20:21], v[20:21], v[22:23]
	v_pk_mul_f32 v[24:25], v[24:25], v[72:73] op_sel_hi:[1,0]
	v_cvt_pk_bf16_f32 v19, v20, v21
	global_store_dwordx2 v[50:51], v[18:19], off offset:144
	global_load_dwordx2 v[22:23], v[76:77], off offset:160
	s_nop 0
	global_load_dwordx4 v[18:21], v[74:75], off offset:320
	s_waitcnt vmcnt(0)
	v_pk_mul_f32 v[18:19], v[24:25], v[18:19]
	v_lshlrev_b32_e32 v24, 16, v22
	v_and_b32_e32 v25, 0xffff0000, v22
	v_pk_mul_f32 v[18:19], v[18:19], v[24:25]
	v_pk_add_f32 v[24:25], v[28:29], v[70:71] op_sel:[0,1] neg_lo:[0,1] neg_hi:[0,1]
	v_lshlrev_b32_e32 v22, 16, v23
	v_pk_mul_f32 v[24:25], v[24:25], v[72:73] op_sel_hi:[1,0]
	v_and_b32_e32 v23, 0xffff0000, v23
	v_pk_mul_f32 v[20:21], v[24:25], v[20:21]
	v_cvt_pk_bf16_f32 v18, v18, v19
	v_pk_mul_f32 v[20:21], v[20:21], v[22:23]
	v_pk_add_f32 v[24:25], v[30:31], v[70:71] op_sel:[0,1] neg_lo:[0,1] neg_hi:[0,1]
	v_cvt_pk_bf16_f32 v19, v20, v21
	global_store_dwordx2 v[50:51], v[18:19], off offset:160
	global_load_dwordx2 v[22:23], v[76:77], off offset:176
	s_nop 0
	global_load_dwordx4 v[18:21], v[74:75], off offset:352
	v_pk_mul_f32 v[24:25], v[24:25], v[72:73] op_sel_hi:[1,0]
	s_waitcnt vmcnt(0)
	v_pk_mul_f32 v[18:19], v[24:25], v[18:19]
	v_lshlrev_b32_e32 v24, 16, v22
	v_and_b32_e32 v25, 0xffff0000, v22
	v_pk_mul_f32 v[18:19], v[18:19], v[24:25]
	v_pk_add_f32 v[24:25], v[32:33], v[70:71] op_sel:[0,1] neg_lo:[0,1] neg_hi:[0,1]
	v_lshlrev_b32_e32 v22, 16, v23
	v_pk_mul_f32 v[24:25], v[24:25], v[72:73] op_sel_hi:[1,0]
	v_and_b32_e32 v23, 0xffff0000, v23
	v_pk_mul_f32 v[20:21], v[24:25], v[20:21]
	v_cvt_pk_bf16_f32 v18, v18, v19
	v_pk_mul_f32 v[20:21], v[20:21], v[22:23]
	s_nop 0
	v_cvt_pk_bf16_f32 v19, v20, v21
	global_store_dwordx2 v[50:51], v[18:19], off offset:176
	global_load_dwordx2 v[22:23], v[76:77], off offset:192
	s_nop 0
	global_load_dwordx4 v[18:21], v[74:75], off offset:384
	s_waitcnt vmcnt(0)
	v_pk_mul_f32 v[2:3], v[2:3], v[18:19]
	v_lshlrev_b32_e32 v18, 16, v22
	v_and_b32_e32 v19, 0xffff0000, v22
	v_pk_mul_f32 v[2:3], v[2:3], v[18:19]
	v_pk_mul_f32 v[4:5], v[4:5], v[20:21]
	v_lshlrev_b32_e32 v18, 16, v23
	v_and_b32_e32 v19, 0xffff0000, v23
	v_pk_mul_f32 v[4:5], v[4:5], v[18:19]
	v_cvt_pk_bf16_f32 v2, v2, v3
	v_cvt_pk_bf16_f32 v3, v4, v5
	global_store_dwordx2 v[50:51], v[2:3], off offset:192
	global_load_dwordx2 v[18:19], v[76:77], off offset:208
	s_nop 0
	global_load_dwordx4 v[2:5], v[74:75], off offset:416
	s_waitcnt vmcnt(0)
	v_pk_mul_f32 v[2:3], v[6:7], v[2:3]
	v_lshlrev_b32_e32 v6, 16, v18
	v_and_b32_e32 v7, 0xffff0000, v18
	v_pk_mul_f32 v[2:3], v[2:3], v[6:7]
	v_pk_add_f32 v[6:7], v[8:9], v[70:71] op_sel:[0,1] neg_lo:[0,1] neg_hi:[0,1]
	v_cvt_pk_bf16_f32 v2, v2, v3
	v_pk_mul_f32 v[6:7], v[6:7], v[72:73] op_sel_hi:[1,0]
	v_pk_add_f32 v[8:9], v[10:11], v[70:71] op_sel:[0,1] neg_lo:[0,1] neg_hi:[0,1]
	v_pk_mul_f32 v[4:5], v[6:7], v[4:5]
	v_lshlrev_b32_e32 v6, 16, v19
	v_and_b32_e32 v7, 0xffff0000, v19
	v_pk_mul_f32 v[4:5], v[4:5], v[6:7]
	v_pk_mul_f32 v[8:9], v[8:9], v[72:73] op_sel_hi:[1,0]
	v_cvt_pk_bf16_f32 v3, v4, v5
	global_store_dwordx2 v[50:51], v[2:3], off offset:208
	global_load_dwordx2 v[6:7], v[76:77], off offset:224
	s_nop 0
	global_load_dwordx4 v[2:5], v[74:75], off offset:448
	s_waitcnt vmcnt(0)
	v_pk_mul_f32 v[2:3], v[8:9], v[2:3]
	v_lshlrev_b32_e32 v8, 16, v6
	v_and_b32_e32 v9, 0xffff0000, v6
	v_pk_mul_f32 v[2:3], v[2:3], v[8:9]
	v_pk_add_f32 v[8:9], v[12:13], v[70:71] op_sel:[0,1] neg_lo:[0,1] neg_hi:[0,1]
	v_lshlrev_b32_e32 v6, 16, v7
	v_pk_mul_f32 v[8:9], v[8:9], v[72:73] op_sel_hi:[1,0]
	v_and_b32_e32 v7, 0xffff0000, v7
	v_pk_mul_f32 v[4:5], v[8:9], v[4:5]
	v_cvt_pk_bf16_f32 v2, v2, v3
	v_pk_mul_f32 v[4:5], v[4:5], v[6:7]
	v_pk_add_f32 v[8:9], v[14:15], v[70:71] op_sel:[0,1] neg_lo:[0,1] neg_hi:[0,1]
	v_cvt_pk_bf16_f32 v3, v4, v5
	global_store_dwordx2 v[50:51], v[2:3], off offset:224
	global_load_dwordx2 v[6:7], v[76:77], off offset:240
	s_nop 0
	global_load_dwordx4 v[2:5], v[74:75], off offset:480
	v_pk_mul_f32 v[8:9], v[8:9], v[72:73] op_sel_hi:[1,0]
	s_waitcnt vmcnt(0)
	v_pk_mul_f32 v[2:3], v[8:9], v[2:3]
	v_lshlrev_b32_e32 v8, 16, v6
	v_and_b32_e32 v9, 0xffff0000, v6
	v_pk_mul_f32 v[2:3], v[2:3], v[8:9]
	v_pk_add_f32 v[8:9], v[16:17], v[70:71] op_sel:[0,1] neg_lo:[0,1] neg_hi:[0,1]
	v_lshlrev_b32_e32 v6, 16, v7
	v_pk_mul_f32 v[8:9], v[8:9], v[72:73] op_sel_hi:[1,0]
	v_and_b32_e32 v7, 0xffff0000, v7
	v_pk_mul_f32 v[4:5], v[8:9], v[4:5]
	v_cvt_pk_bf16_f32 v2, v2, v3
	v_pk_mul_f32 v[4:5], v[4:5], v[6:7]
	s_nop 0
	v_cvt_pk_bf16_f32 v3, v4, v5
	global_store_dwordx2 v[50:51], v[2:3], off offset:240
	s_cbranch_scc0 .LBB0_1246

; __device__ __forceinline__ int crow(int r, int hi) { return (r & 3) + 8 * (r >> 2) + 4 * hi; }
; #define MFMA32(a, b, c) __builtin_amdgcn_mfma_f32_32x32x16_bf16((a), (b), (c), 0, 0, 0)
; __device__ __forceinline__ void ro_item2(int it0, LAS unsigned char* lds, const bf16_t* RQ, const bf16_t* RK, const bf16_t* RV, const bf16_t* RG, const bf16_t* SPREV, const float* GN, bf16_t* MIX,
;                                          int tid, int wid, int lane) {
;     ...
;     for (int jt = 0; jt <= ct; ++jt) {
;         f32x16 st = {};
;         const bf16_t* kptr = RK + (r0 + 32 * jt + x) * 1024 + h * 128 + 8 * hi;
; #pragma unroll
;         for (int ks = 0; ks < 8; ++ks) st = MFMA32(*(const bf16x8*)(kptr + 16 * ks), qf[ks], st);
;         if (jt == ct) {
; #pragma unroll
;             for (int r = 0; r < 16; ++r) if (crow(r, hi) > x) st[r] = 0.f;
;         }
; #pragma unroll
;         for (int s2 = 0; s2 < 2; ++s2) {
;             const bf16x8 pb = pack8(st, s2);
; #pragma unroll
;             for (int et = 0; et < 4; ++et) o[et] = MFMA32(lds_cat_sw<VS>(VT, 32 * et + x, 32 * jt + 16 * s2 + 4 * hi), pb, o[et]);
;         }
;     }
.LBB0_1245:
	global_load_dwordx4 v[220:223], v[146:147], off offset:-128
	global_load_dwordx4 v[224:227], v[146:147], off offset:-96
	global_load_dwordx4 v[228:231], v[146:147], off offset:-64
	global_load_dwordx4 v[232:235], v[146:147], off offset:-32
	global_load_dwordx4 v[236:239], v[146:147], off
	global_load_dwordx4 v[240:243], v[146:147], off offset:32
	global_load_dwordx4 v[244:247], v[146:147], off offset:64
	global_load_dwordx4 v[248:251], v[146:147], off offset:96
	v_lshl_add_u64 v[146:147], v[146:147], 0, s[60:61]
	v_add_u32_e32 v176, 8, v175
	s_add_i32 s46, s46, -1
	s_cmp_lg_u32 s46, 0
	s_waitcnt vmcnt(7)
	v_mfma_f32_32x32x16_bf16 v[66:81], v[220:223], v[110:113], 0
	s_waitcnt vmcnt(6)
	v_mfma_f32_32x32x16_bf16 v[66:81], v[224:227], v[106:109], v[66:81]
	s_waitcnt vmcnt(5)
	v_mfma_f32_32x32x16_bf16 v[66:81], v[228:231], v[102:105], v[66:81]
	s_waitcnt vmcnt(4)
	v_mfma_f32_32x32x16_bf16 v[66:81], v[232:235], v[98:101], v[66:81]
	s_waitcnt vmcnt(3)
	v_mfma_f32_32x32x16_bf16 v[66:81], v[236:239], v[94:97], v[66:81]
	s_waitcnt vmcnt(2)
	v_mfma_f32_32x32x16_bf16 v[66:81], v[240:243], v[90:93], v[66:81]
	s_waitcnt vmcnt(1)
	v_mfma_f32_32x32x16_bf16 v[66:81], v[244:247], v[86:89], v[66:81]
	s_waitcnt vmcnt(0)
	v_mfma_f32_32x32x16_bf16 v[66:81], v[248:251], v[82:85], v[66:81]
	s_nop 11
	v_cvt_pk_bf16_f32 v66, v66, v67
	v_cvt_pk_bf16_f32 v67, v68, v69
	v_cvt_pk_bf16_f32 v69, v72, v73
	v_xor_b32_e32 v72, v176, v123
	v_lshl_add_u32 v72, v72, 1, v149
	v_cvt_pk_bf16_f32 v68, v70, v71
	ds_read_b64 v[70:71], v141
	ds_read_b64 v[72:73], v72
	s_waitcnt lgkmcnt(0)
	v_mfma_f32_32x32x16_bf16 v[50:65], v[70:73], v[66:69], v[50:65]
	v_xor_b32_e32 v70, v175, v129
	v_xor_b32_e32 v72, v176, v129
	v_lshl_add_u32 v70, v70, 1, v152
	v_lshl_add_u32 v72, v72, 1, v152
	ds_read_b64 v[70:71], v70
	ds_read_b64 v[72:73], v72
	v_add_u32_e32 v141, 64, v141
	s_waitcnt lgkmcnt(0)
	v_mfma_f32_32x32x16_bf16 v[34:49], v[70:73], v[66:69], v[34:49]
	v_xor_b32_e32 v70, v175, v154
	v_xor_b32_e32 v72, v176, v154
	v_lshl_add_u32 v70, v70, 1, v153
	v_lshl_add_u32 v72, v72, 1, v153
	ds_read_b64 v[70:71], v70
	ds_read_b64 v[72:73], v72
	s_waitcnt lgkmcnt(0)
	v_mfma_f32_32x32x16_bf16 v[18:33], v[70:73], v[66:69], v[18:33]
	v_xor_b32_e32 v70, v175, v156
	v_xor_b32_e32 v72, v176, v156
	v_lshl_add_u32 v70, v70, 1, v155
	v_lshl_add_u32 v72, v72, 1, v155
	ds_read_b64 v[70:71], v70
	ds_read_b64 v[72:73], v72
	s_waitcnt lgkmcnt(0)
	v_mfma_f32_32x32x16_bf16 v[2:17], v[70:73], v[66:69], v[2:17]
	v_cvt_pk_bf16_f32 v66, v74, v75
	v_add_u32_e32 v74, 16, v175
	v_add_u32_e32 v75, 24, v175
	v_xor_b32_e32 v70, v74, v123
	v_xor_b32_e32 v72, v75, v123
	v_lshl_add_u32 v70, v70, 1, v149
	v_lshl_add_u32 v72, v72, 1, v149
	ds_read_b64 v[70:71], v70
	ds_read_b64 v[72:73], v72
	v_cvt_pk_bf16_f32 v67, v76, v77
	v_cvt_pk_bf16_f32 v68, v78, v79
	v_cvt_pk_bf16_f32 v69, v80, v81
	v_add_u32_e32 v175, 32, v175
	s_waitcnt lgkmcnt(0)
	v_mfma_f32_32x32x16_bf16 v[50:65], v[70:73], v[66:69], v[50:65]
	v_xor_b32_e32 v70, v74, v129
	v_xor_b32_e32 v72, v75, v129
	v_lshl_add_u32 v70, v70, 1, v152
	v_lshl_add_u32 v72, v72, 1, v152
	ds_read_b64 v[70:71], v70
	ds_read_b64 v[72:73], v72
	s_waitcnt lgkmcnt(0)
	v_mfma_f32_32x32x16_bf16 v[34:49], v[70:73], v[66:69], v[34:49]
	v_xor_b32_e32 v70, v74, v154
	v_xor_b32_e32 v72, v75, v154
	v_lshl_add_u32 v70, v70, 1, v153
	v_lshl_add_u32 v72, v72, 1, v153
	ds_read_b64 v[70:71], v70
	ds_read_b64 v[72:73], v72
	s_waitcnt lgkmcnt(0)
	v_mfma_f32_32x32x16_bf16 v[18:33], v[70:73], v[66:69], v[18:33]
	v_xor_b32_e32 v70, v74, v156
	v_xor_b32_e32 v72, v75, v156
	v_lshl_add_u32 v70, v70, 1, v155
	v_lshl_add_u32 v72, v72, 1, v155
	ds_read_b64 v[70:71], v70
	ds_read_b64 v[72:73], v72
	s_waitcnt lgkmcnt(0)
	v_mfma_f32_32x32x16_bf16 v[2:17], v[70:73], v[66:69], v[2:17]
	s_cbranch_scc1 .LBB0_1245
	s_branch .LBB0_1219

; __global__ void __launch_bounds__(512, 2) mk_fwd(Args a) {
	.amdhsa_kernel _Z6mk_fwd4Args
		.amdhsa_group_segment_fixed_size 0
		.amdhsa_private_segment_fixed_size 0
		.amdhsa_kernarg_size 456
		.amdhsa_user_sgpr_count 2
		.amdhsa_user_sgpr_dispatch_ptr 0
		.amdhsa_user_sgpr_queue_ptr 0
		.amdhsa_user_sgpr_kernarg_segment_ptr 1
		.amdhsa_user_sgpr_dispatch_id 0
		.amdhsa_user_sgpr_kernarg_preload_length 0
		.amdhsa_user_sgpr_kernarg_preload_offset 0
		.amdhsa_user_sgpr_private_segment_size 0
		.amdhsa_uses_dynamic_stack 0
		.amdhsa_enable_private_segment 0
		.amdhsa_system_sgpr_workgroup_id_x 1
		.amdhsa_system_sgpr_workgroup_id_y 0
		.amdhsa_system_sgpr_workgroup_id_z 0
		.amdhsa_system_sgpr_workgroup_info 0
		.amdhsa_system_vgpr_workitem_id 2
		.amdhsa_next_free_vgpr 256
		.amdhsa_next_free_sgpr 102
		.amdhsa_accum_offset 256
		.amdhsa_reserve_vcc 1
		.amdhsa_float_round_mode_32 0
		.amdhsa_float_round_mode_16_64 0
		.amdhsa_float_denorm_mode_32 3
		.amdhsa_float_denorm_mode_16_64 3
		.amdhsa_dx10_clamp 1
		.amdhsa_ieee_mode 1
		.amdhsa_fp16_overflow 0
		.amdhsa_tg_split 0
		.amdhsa_exception_fp_ieee_invalid_op 0
		.amdhsa_exception_fp_denorm_src 0
		.amdhsa_exception_fp_ieee_div_zero 0
		.amdhsa_exception_fp_ieee_overflow 0
		.amdhsa_exception_fp_ieee_underflow 0
		.amdhsa_exception_fp_ieee_inexact 0
		.amdhsa_exception_int_div_zero 0
	.end_amdhsa_kernel

; __global__ void __launch_bounds__(512, 2) mk_fwd(Args a) {
.Lfunc_end0:
	.size	_Z6mk_fwd4Args, .Lfunc_end0-_Z6mk_fwd4Args
	.set _Z6mk_fwd4Args.num_vgpr, 256
	.set _Z6mk_fwd4Args.num_agpr, 0
	.set _Z6mk_fwd4Args.numbered_sgpr, 102
	.set _Z6mk_fwd4Args.num_named_barrier, 0
	.set _Z6mk_fwd4Args.private_seg_size, 0
	.set _Z6mk_fwd4Args.uses_vcc, 1
	.set _Z6mk_fwd4Args.uses_flat_scratch, 0
	.set _Z6mk_fwd4Args.has_dyn_sized_stack, 0
	.set _Z6mk_fwd4Args.has_recursion, 0
	.set _Z6mk_fwd4Args.has_indirect_call, 0

; __global__ void __launch_bounds__(512, 2) mk_fwd(Args a) {
amdhsa.kernels:
  - .agpr_count:     0
    .args:
      - .offset:         0
        .size:           200
        .value_kind:     by_value
      - .offset:         200
        .size:           4
        .value_kind:     hidden_block_count_x
      - .offset:         204
        .size:           4
        .value_kind:     hidden_block_count_y
      - .offset:         208
        .size:           4
        .value_kind:     hidden_block_count_z
      - .offset:         212
        .size:           2
        .value_kind:     hidden_group_size_x
      - .offset:         214
        .size:           2
        .value_kind:     hidden_group_size_y
      - .offset:         216
        .size:           2
        .value_kind:     hidden_group_size_z
      - .offset:         218
        .size:           2
        .value_kind:     hidden_remainder_x
      - .offset:         220
        .size:           2
        .value_kind:     hidden_remainder_y
      - .offset:         222
        .size:           2
        .value_kind:     hidden_remainder_z
      - .offset:         240
        .size:           8
        .value_kind:     hidden_global_offset_x
      - .offset:         248
        .size:           8
        .value_kind:     hidden_global_offset_y
      - .offset:         256
        .size:           8
        .value_kind:     hidden_global_offset_z
      - .offset:         264
        .size:           2
        .value_kind:     hidden_grid_dims
      - .offset:         288
        .size:           8
        .value_kind:     hidden_multigrid_sync_arg
      - .offset:         320
        .size:           4
        .value_kind:     hidden_dynamic_lds_size
    .group_segment_fixed_size: 0
    .kernarg_segment_align: 8
    .kernarg_segment_size: 456
    .language:       OpenCL C
    .language_version:
      - 2
      - 0
    .max_flat_workgroup_size: 512
    .name:           _Z6mk_fwd4Args
    .private_segment_fixed_size: 0
    .sgpr_count:     108
    .sgpr_spill_count: 109
    .symbol:         _Z6mk_fwd4Args.kd
    .uniform_work_group_size: 1
    .uses_dynamic_stack: false
    .vgpr_count:     256
    .vgpr_spill_count: 0
    .wavefront_size: 64
